# S5 pass-2: output product moved to v_mfma_f32_16x16x4_f32 (f32 in/acc), C-matrix and chunk-start state loads issued together instead of one wait per load
# speedup vs baseline: 1.0104x; 1.0084x over previous
; __device__ __forceinline__ int bidx() { int b = blockIdx.x; asm volatile("" : "+s"(b)); return b; }
; #define LAS __attribute__((address_space(3)))
; template <int PASS>
; __device__ __forceinline__ void s5_scan(const Params& p, int l, int widx, int nw, int beff, int nblk, int lane, LAS unsigned char* lds) {
;     if (widx < 0 || widx >= nw || beff < 0) return;
;     unsigned char* ws = p.ws;
;     LAS float* ub = (LAS float*)(lds + widx * 19456);
;     LAS float* xb = ub + 512;
;     LAS float* ct = xb + 16 * 132;
;     const float* ZS = (const float*)(ws + WS_ZS); const float* tab = (const float*)(ws + WS_S5TAB + (size_t)l * SZ_S5TAB);
;     float* XE = (float*)(ws + WS_XE);
;     float* YS = (float*)(ws + WS_YS); bf16_t* YSB = (bf16_t*)(ws + WS_YSB);
;     for (int u = widx * nblk + beff; u < 1024; u += nw * nblk) {
;         const int c = u & 15, g = (u >> 4) & 31, b = u >> 9; const int gn = g * 64 + lane;
; __global__ void __launch_bounds__(512, 2) mk_fwd(Params p) {
;     ...
;                 s5_scan<2>(p, l, (wave == 3) ? 0 : ((wave == 7) ? 1 : -1), 2, bidx(), gridDim.x, lane, lds + 24576);
.LBB0_324:
	v_readlane_b32 s1, v254, 17
	s_cmp_eq_u32 s1, 7
	s_cselect_b32 s0, 1, -1
	s_cmp_eq_u32 s1, 4
	s_cselect_b32 s0, 2, s0
	s_cmp_eq_u32 s1, 5
	s_cselect_b32 s0, 3, s0
	s_cmp_lg_u32 s1, 3
	s_cselect_b32 s0, s0, 0
	s_mov_b32 s1, s2
	s_or_b32 s4, s1, s0
	s_cmp_lt_i32 s4, 0
	v_mov_b64_e32 v[196:197], v[142:143]
	v_mov_b32_e32 v143, v190
	v_mov_b32_e32 v192, 0xfcf
	v_not_b32_e32 v193, 63
	s_cbranch_scc1 .LBB0_356
	v_readlane_b32 s4, v253, 5
	s_mul_i32 s4, s0, s4
	s_add_i32 s6, s1, s4
	s_cmpk_gt_i32 s6, 0x3ff
	v_readlane_b32 s5, v253, 6
	s_cbranch_scc1 .LBB0_356
	s_mulk_i32 s0, 0x4c00
	v_readlane_b32 s4, v255, 18
	s_add_i32 s7, s0, 0
	s_lshl_b64 s[0:1], s[86:87], 15
	v_readlane_b32 s5, v255, 19
	v_readlane_b32 s8, v253, 17
	v_lshlrev_b32_e32 v0, 2, v201
	s_lshl_b64 s[4:5], s[4:5], 2
	v_readlane_b32 s10, v253, 19
	v_or_b32_e32 v44, s0, v201
	v_mov_b32_e32 v45, s1
	v_and_b32_e32 v46, 12, v0
	v_readlane_b32 s0, v251, 40
	v_readlane_b32 s11, v253, 20
	s_add_u32 s4, s10, s4
	v_lshlrev_b32_e32 v136, 2, v46
	v_readlane_b32 s1, v251, 41
	s_addc_u32 s5, s11, s5
	v_readlane_b32 s12, v253, 21
	v_lshl_add_u64 v[48:49], s[0:1], 0, v[136:137]
	s_add_i32 s0, s7, 0x6800
	s_add_i32 s1, s7, 0x8900
	v_and_b32_e32 v134, 15, v201
	v_lshrrev_b32_e32 v135, 4, v201
	v_mul_u32_u24_e32 v138, 0x210, v134
	v_lshl_add_u32 v138, v135, 4, v138
	v_lshl_add_u32 v135, v135, 6, v134
	v_add_u32_e32 v134, s0, v138
	v_lshl_add_u32 v135, v135, 2, s0
	v_lshl_add_u32 v138, v201, 4, s0
	v_readlane_b32 s13, v253, 22
	v_readlane_b32 s14, v253, 23
	v_readlane_b32 s15, v253, 24
	v_add_u32_e32 v72, s7, v0
	v_add_u32_e32 v73, s0, v0
	v_mov_b32_e32 v0, s1
	s_movk_i32 s1, 0x210
	v_readlane_b32 s9, v253, 18
	v_lshrrev_b32_e32 v65, 2, v201
	v_mad_u32_u24 v74, v46, s1, v0
	v_mov_b32_e32 v0, s0
	v_readlane_b32 s12, v253, 41
	v_lshlrev_b32_e32 v47, 1, v201
	v_lshlrev_b32_e32 v70, 4, v201
	v_lshlrev_b32_e32 v71, 6, v65
	v_lshl_add_u64 v[50:51], s[4:5], 0, v[136:137]
	s_add_i32 s8, s7, 0x6000
	v_mad_u32_u24 v75, v65, s1, v0
	s_mov_b32 s9, s6
	v_readlane_b32 s26, v253, 55
	v_readlane_b32 s27, v253, 56
	v_readlane_b32 s13, v253, 42
	v_readlane_b32 s14, v253, 43
	v_readlane_b32 s15, v253, 44
	v_readlane_b32 s16, v253, 45
	v_readlane_b32 s17, v253, 46
	v_readlane_b32 s18, v253, 47
	v_readlane_b32 s19, v253, 48
	v_readlane_b32 s20, v253, 49
	v_readlane_b32 s21, v253, 50
	v_readlane_b32 s22, v253, 51
	v_readlane_b32 s23, v253, 52
	v_readlane_b32 s24, v253, 53
	v_readlane_b32 s25, v253, 54
	s_branch .LBB0_328

; template <int PASS>
; __device__ __forceinline__ void s5_scan(const Params& p, int l, int widx, int nw, int beff, int nblk, int lane, LAS unsigned char* lds) {
;     ...
;         const int c = u & 15, g = (u >> 4) & 31, b = u >> 9; const int gn = g * 64 + lane;
;         const float ar = tab[gn * 2], ai = tab[gn * 2 + 1];
;         float br[16], bi[16];
; #pragma unroll
;         for (int q = 0; q < 8; ++q) { const f32x4 v = *(const f32x4*)(tab + 4096 + gn * 32 + q * 4); br[2 * q] = v.x; bi[2 * q] = v.y; br[2 * q + 1] = v.z; bi[2 * q + 1] = v.w; }
;         float xr = 0.f, xi = 0.f;
;         if (PASS == 2) {
;             float pr = ar, pi = ai;
; #pragma unroll
;             for (int i = 0; i < 8; ++i) { const float r2 = pr * pr - pi * pi, i2 = 2.f * pr * pi; pr = r2; pi = i2; }
;             for (int cp = 0; cp < c; ++cp) { const int up = (u & ~15) + cp; const float er = XE[(up * 64 + lane) * 2], ei = XE[(up * 64 + lane) * 2 + 1];
;                 const float nr = pr * xr - pi * xi + er, ni = pr * xi + pi * xr + ei; xr = nr; xi = ni; }
.LBB0_328:
	s_bfe_u32 s0, s6, 0x50004
	v_lshl_or_b32 v0, s0, 6, v201
	v_readlane_b32 s10, v254, 22
	v_readlane_b32 s4, v254, 20
	v_lshlrev_b32_e32 v8, 3, v0
	v_lshlrev_b32_e32 v28, 7, v0
	v_readlane_b32 s11, v254, 23
	v_readlane_b32 s5, v254, 21
	s_nop 3
	global_load_dwordx4 v[0:3], v28, s[10:11] offset:32
	global_load_dwordx4 v[4:7], v28, s[10:11] offset:16
	global_load_dwordx2 v[52:53], v8, s[4:5]
	s_nop 0
	global_load_dwordx4 v[8:11], v28, s[10:11]
	global_load_dwordx4 v[12:15], v28, s[10:11] offset:112
	global_load_dwordx4 v[16:19], v28, s[10:11] offset:96
	global_load_dwordx4 v[20:23], v28, s[10:11] offset:80
	global_load_dwordx4 v[24:27], v28, s[10:11] offset:48
	s_nop 0
	global_load_dwordx4 v[28:31], v28, s[10:11] offset:64
	s_and_b32 s1, s6, 15
	s_cmp_eq_u32 s1, 0
	s_cbranch_scc1 .LBB0_331
	s_lshr_b32 s5, s6, 4
	v_lshl_or_b32 v32, s5, 11, v47
	v_ashrrev_i32_e32 v33, 31, v32
	v_lshl_add_u64 v[38:39], v[32:33], 2, s[48:49]
	s_nop 0
	v_add_co_u32_e32 v40, vcc, 0x1000, v38
	s_nop 1
	v_addc_co_u32_e32 v41, vcc, 0, v39, vcc
	global_load_dwordx2 v[106:107], v[38:39], off
	global_load_dwordx2 v[108:109], v[38:39], off offset:512
	global_load_dwordx2 v[110:111], v[38:39], off offset:1024
	global_load_dwordx2 v[112:113], v[38:39], off offset:1536
	global_load_dwordx2 v[114:115], v[38:39], off offset:2048
	global_load_dwordx2 v[116:117], v[38:39], off offset:2560
	global_load_dwordx2 v[118:119], v[38:39], off offset:3072
	global_load_dwordx2 v[120:121], v[38:39], off offset:3584
	global_load_dwordx2 v[122:123], v[40:41], off
	global_load_dwordx2 v[124:125], v[40:41], off offset:512
	global_load_dwordx2 v[126:127], v[40:41], off offset:1024
	global_load_dwordx2 v[128:129], v[40:41], off offset:1536
	global_load_dwordx2 v[130:131], v[40:41], off offset:2048
	global_load_dwordx2 v[132:133], v[40:41], off offset:2560
	global_load_dwordx2 v[148:149], v[40:41], off offset:3072
	s_waitcnt vmcnt(15)
	v_pk_mul_f32 v[34:35], v[52:53], v[52:53]
	v_add_f32_e32 v33, v52, v52
	v_sub_f32_e32 v34, v34, v35
	v_mul_f32_e32 v33, v53, v33
	v_add_f32_e32 v35, v34, v34
	v_mul_f32_e32 v34, v34, v34
	v_mul_f32_e32 v35, v33, v35
	v_fma_f32 v33, -v33, v33, v34
	v_add_f32_e32 v34, v33, v33
	v_mul_f32_e32 v34, v35, v34
	v_mul_f32_e32 v35, v35, v35
	v_fma_f32 v33, v33, v33, -v35
	v_add_f32_e32 v35, v33, v33
	v_mul_f32_e32 v35, v34, v35
	v_mul_f32_e32 v34, v34, v34
	v_fma_f32 v33, v33, v33, -v34
	v_add_f32_e32 v34, v33, v33
	v_mul_f32_e32 v34, v35, v34
	v_mul_f32_e32 v35, v35, v35
	v_fma_f32 v33, v33, v33, -v35
	v_add_f32_e32 v35, v33, v33
	v_mul_f32_e32 v35, v34, v35
	v_mul_f32_e32 v34, v34, v34
	v_fma_f32 v33, v33, v33, -v34
	v_add_f32_e32 v34, v33, v33
	v_mul_f32_e32 v36, v35, v34
	v_mul_f32_e32 v34, v35, v35
	v_fma_f32 v33, v33, v33, -v34
	v_add_f32_e32 v34, v33, v33
	v_mul_f32_e32 v35, v36, v36
	v_mul_f32_e32 v34, v36, v34
	v_fma_f32 v36, v33, v33, -v35
	v_mov_b32_e32 v54, 0
	s_and_b32 s4, s9, 15
	v_mov_b32_e32 v37, v36
	v_mov_b32_e32 v35, v34
	v_mov_b32_e32 v55, v54
	s_waitcnt vmcnt(0)
	v_pk_mul_f32 v[40:41], v[34:35], v[54:55] op_sel:[0,1] op_sel_hi:[1,0]
	s_nop 0
	v_pk_fma_f32 v[42:43], v[36:37], v[54:55], v[40:41] neg_lo:[0,0,1] neg_hi:[0,0,1]
	v_pk_fma_f32 v[40:41], v[36:37], v[54:55], v[40:41]
	s_nop 0
	v_mov_b32_e32 v43, v41
	s_cmp_eq_u32 s4, 1
	v_pk_add_f32 v[54:55], v[42:43], v[106:107]
	s_cbranch_scc1 .Ls5_hdone
	v_pk_mul_f32 v[40:41], v[34:35], v[54:55] op_sel:[0,1] op_sel_hi:[1,0]
	s_nop 0
	v_pk_fma_f32 v[42:43], v[36:37], v[54:55], v[40:41] neg_lo:[0,0,1] neg_hi:[0,0,1]
	v_pk_fma_f32 v[40:41], v[36:37], v[54:55], v[40:41]
	s_nop 0
	v_mov_b32_e32 v43, v41
	s_cmp_eq_u32 s4, 2
	v_pk_add_f32 v[54:55], v[42:43], v[108:109]
	s_cbranch_scc1 .Ls5_hdone
	v_pk_mul_f32 v[40:41], v[34:35], v[54:55] op_sel:[0,1] op_sel_hi:[1,0]
	s_nop 0
	v_pk_fma_f32 v[42:43], v[36:37], v[54:55], v[40:41] neg_lo:[0,0,1] neg_hi:[0,0,1]
	v_pk_fma_f32 v[40:41], v[36:37], v[54:55], v[40:41]
	s_nop 0
	v_mov_b32_e32 v43, v41
	s_cmp_eq_u32 s4, 3
	v_pk_add_f32 v[54:55], v[42:43], v[110:111]
	s_cbranch_scc1 .Ls5_hdone
	v_pk_mul_f32 v[40:41], v[34:35], v[54:55] op_sel:[0,1] op_sel_hi:[1,0]
	s_nop 0
	v_pk_fma_f32 v[42:43], v[36:37], v[54:55], v[40:41] neg_lo:[0,0,1] neg_hi:[0,0,1]
	v_pk_fma_f32 v[40:41], v[36:37], v[54:55], v[40:41]
	s_nop 0
	v_mov_b32_e32 v43, v41
	s_cmp_eq_u32 s4, 4
	v_pk_add_f32 v[54:55], v[42:43], v[112:113]
	s_cbranch_scc1 .Ls5_hdone
	v_pk_mul_f32 v[40:41], v[34:35], v[54:55] op_sel:[0,1] op_sel_hi:[1,0]
	s_nop 0
	v_pk_fma_f32 v[42:43], v[36:37], v[54:55], v[40:41] neg_lo:[0,0,1] neg_hi:[0,0,1]
	v_pk_fma_f32 v[40:41], v[36:37], v[54:55], v[40:41]
	s_nop 0
	v_mov_b32_e32 v43, v41
	s_cmp_eq_u32 s4, 5
	v_pk_add_f32 v[54:55], v[42:43], v[114:115]
	s_cbranch_scc1 .Ls5_hdone
	v_pk_mul_f32 v[40:41], v[34:35], v[54:55] op_sel:[0,1] op_sel_hi:[1,0]
	s_nop 0
	v_pk_fma_f32 v[42:43], v[36:37], v[54:55], v[40:41] neg_lo:[0,0,1] neg_hi:[0,0,1]
	v_pk_fma_f32 v[40:41], v[36:37], v[54:55], v[40:41]
	s_nop 0
	v_mov_b32_e32 v43, v41
	s_cmp_eq_u32 s4, 6
	v_pk_add_f32 v[54:55], v[42:43], v[116:117]
	s_cbranch_scc1 .Ls5_hdone
	v_pk_mul_f32 v[40:41], v[34:35], v[54:55] op_sel:[0,1] op_sel_hi:[1,0]
	s_nop 0
	v_pk_fma_f32 v[42:43], v[36:37], v[54:55], v[40:41] neg_lo:[0,0,1] neg_hi:[0,0,1]
	v_pk_fma_f32 v[40:41], v[36:37], v[54:55], v[40:41]
	s_nop 0
	v_mov_b32_e32 v43, v41
	s_cmp_eq_u32 s4, 7
	v_pk_add_f32 v[54:55], v[42:43], v[118:119]
	s_cbranch_scc1 .Ls5_hdone
	v_pk_mul_f32 v[40:41], v[34:35], v[54:55] op_sel:[0,1] op_sel_hi:[1,0]
	s_nop 0
	v_pk_fma_f32 v[42:43], v[36:37], v[54:55], v[40:41] neg_lo:[0,0,1] neg_hi:[0,0,1]
	v_pk_fma_f32 v[40:41], v[36:37], v[54:55], v[40:41]
	s_nop 0
	v_mov_b32_e32 v43, v41
	s_cmp_eq_u32 s4, 8
	v_pk_add_f32 v[54:55], v[42:43], v[120:121]
	s_cbranch_scc1 .Ls5_hdone
; template <int PASS>
; __device__ __forceinline__ void s5_scan(const Params& p, int l, int widx, int nw, int beff, int nblk, int lane, LAS unsigned char* lds) {
;     ...
;         if (PASS == 2) {
;             float pr = ar, pi = ai;
; #pragma unroll
;             for (int i = 0; i < 8; ++i) { const float r2 = pr * pr - pi * pi, i2 = 2.f * pr * pi; pr = r2; pi = i2; }
;             for (int cp = 0; cp < c; ++cp) { const int up = (u & ~15) + cp; const float er = XE[(up * 64 + lane) * 2], ei = XE[(up * 64 + lane) * 2 + 1];
;                 const float nr = pr * xr - pi * xi + er, ni = pr * xi + pi * xr + ei; xr = nr; xi = ni; }
	v_pk_mul_f32 v[40:41], v[34:35], v[54:55] op_sel:[0,1] op_sel_hi:[1,0]
	s_nop 0
	v_pk_fma_f32 v[42:43], v[36:37], v[54:55], v[40:41] neg_lo:[0,0,1] neg_hi:[0,0,1]
	v_pk_fma_f32 v[40:41], v[36:37], v[54:55], v[40:41]
	s_nop 0
	v_mov_b32_e32 v43, v41
	s_cmp_eq_u32 s4, 9
	v_pk_add_f32 v[54:55], v[42:43], v[122:123]
	s_cbranch_scc1 .Ls5_hdone
	v_pk_mul_f32 v[40:41], v[34:35], v[54:55] op_sel:[0,1] op_sel_hi:[1,0]
	s_nop 0
	v_pk_fma_f32 v[42:43], v[36:37], v[54:55], v[40:41] neg_lo:[0,0,1] neg_hi:[0,0,1]
	v_pk_fma_f32 v[40:41], v[36:37], v[54:55], v[40:41]
	s_nop 0
	v_mov_b32_e32 v43, v41
	s_cmp_eq_u32 s4, 10
	v_pk_add_f32 v[54:55], v[42:43], v[124:125]
	s_cbranch_scc1 .Ls5_hdone
	v_pk_mul_f32 v[40:41], v[34:35], v[54:55] op_sel:[0,1] op_sel_hi:[1,0]
	s_nop 0
	v_pk_fma_f32 v[42:43], v[36:37], v[54:55], v[40:41] neg_lo:[0,0,1] neg_hi:[0,0,1]
	v_pk_fma_f32 v[40:41], v[36:37], v[54:55], v[40:41]
	s_nop 0
	v_mov_b32_e32 v43, v41
	s_cmp_eq_u32 s4, 11
	v_pk_add_f32 v[54:55], v[42:43], v[126:127]
	s_cbranch_scc1 .Ls5_hdone
	v_pk_mul_f32 v[40:41], v[34:35], v[54:55] op_sel:[0,1] op_sel_hi:[1,0]
	s_nop 0
	v_pk_fma_f32 v[42:43], v[36:37], v[54:55], v[40:41] neg_lo:[0,0,1] neg_hi:[0,0,1]
	v_pk_fma_f32 v[40:41], v[36:37], v[54:55], v[40:41]
	s_nop 0
	v_mov_b32_e32 v43, v41
	s_cmp_eq_u32 s4, 12
	v_pk_add_f32 v[54:55], v[42:43], v[128:129]
	s_cbranch_scc1 .Ls5_hdone
	v_pk_mul_f32 v[40:41], v[34:35], v[54:55] op_sel:[0,1] op_sel_hi:[1,0]
	s_nop 0
	v_pk_fma_f32 v[42:43], v[36:37], v[54:55], v[40:41] neg_lo:[0,0,1] neg_hi:[0,0,1]
	v_pk_fma_f32 v[40:41], v[36:37], v[54:55], v[40:41]
	s_nop 0
	v_mov_b32_e32 v43, v41
	s_cmp_eq_u32 s4, 13
	v_pk_add_f32 v[54:55], v[42:43], v[130:131]
	s_cbranch_scc1 .Ls5_hdone
	v_pk_mul_f32 v[40:41], v[34:35], v[54:55] op_sel:[0,1] op_sel_hi:[1,0]
	s_nop 0
	v_pk_fma_f32 v[42:43], v[36:37], v[54:55], v[40:41] neg_lo:[0,0,1] neg_hi:[0,0,1]
	v_pk_fma_f32 v[40:41], v[36:37], v[54:55], v[40:41]
	s_nop 0
	v_mov_b32_e32 v43, v41
	s_cmp_eq_u32 s4, 14
	v_pk_add_f32 v[54:55], v[42:43], v[132:133]
	s_cbranch_scc1 .Ls5_hdone
	v_pk_mul_f32 v[40:41], v[34:35], v[54:55] op_sel:[0,1] op_sel_hi:[1,0]
	s_nop 0
	v_pk_fma_f32 v[42:43], v[36:37], v[54:55], v[40:41] neg_lo:[0,0,1] neg_hi:[0,0,1]
	v_pk_fma_f32 v[40:41], v[36:37], v[54:55], v[40:41]
	s_nop 0
	v_mov_b32_e32 v43, v41
	s_cmp_eq_u32 s4, 15
	v_pk_add_f32 v[54:55], v[42:43], v[148:149]
.Ls5_hdone:
	s_branch .LBB0_332
.LBB0_331:
	v_mov_b32_e32 v136, v137
	v_mov_b64_e32 v[54:55], v[136:137]
; #define LAS __attribute__((address_space(3)))
; __device__ __forceinline__ float dot4(f32x4 a, f32x4 b) { return (a.x * b.x + a.y * b.y) + (a.z * b.z + a.w * b.w); }
; template <int PASS>
; __device__ __forceinline__ void s5_scan(const Params& p, int l, int widx, int nw, int beff, int nblk, int lane, LAS unsigned char* lds) {
;     ...
; #pragma unroll
;             for (int cc = 0; cc < 16; ++cc) { ct[cc * 132 + lane] = p.in[28][((size_t)l * 32 + g) * 1024 + cc * 64 + lane]; ct[cc * 132 + 64 + lane] = -p.in[29][((size_t)l * 32 + g) * 1024 + cc * 64 + lane]; }
;         }
;         const int m0 = b * SEQ + c * 256;
;         f32x4 un = *(const f32x4*)(ZS + (size_t)(m0 + (lane >> 2)) * 512 + g * 16 + (lane & 3) * 4);
;         for (int bt = 0; bt < 16; ++bt) {
;             LAS float* ubc = ub + (bt & 1) * 256;
;             *(LAS f32x4*)(ubc + lane * 4) = un;
;             if (bt + 1 < 16) un = *(const f32x4*)(ZS + (size_t)(m0 + (bt + 1) * 16 + (lane >> 2)) * 512 + g * 16 + (lane & 3) * 4);
;     ...
;                 for (int n4 = 0; n4 < 32; ++n4) {
;                     const f32x4 xv = *(LAS f32x4*)(xb + s * 132 + n4 * 4);
; #pragma unroll
;                     for (int j = 0; j < 4; ++j) { const f32x4 cv = *(LAS f32x4*)(ct + (c4 * 4 + j) * 132 + n4 * 4); y[j] += dot4(xv, cv); }
.LBB0_332:
	v_lshl_or_b32 v32, s0, 10, v44
	v_mov_b32_e32 v33, v45
	v_readlane_b32 s12, v253, 17
	v_lshlrev_b64 v[34:35], 2, v[32:33]
	v_readlane_b32 s13, v253, 18
	v_lshl_add_u64 v[32:33], s[26:27], 0, v[34:35]
	v_lshl_add_u64 v[34:35], s[12:13], 0, v[34:35]
	global_load_dword v76, v[32:33], off
	global_load_dword v77, v[34:35], off
	global_load_dword v78, v[32:33], off offset:256
	global_load_dword v79, v[34:35], off offset:256
	global_load_dword v80, v[32:33], off offset:512
	global_load_dword v81, v[34:35], off offset:512
	global_load_dword v82, v[32:33], off offset:768
	global_load_dword v83, v[34:35], off offset:768
	global_load_dword v84, v[32:33], off offset:1024
	global_load_dword v85, v[34:35], off offset:1024
	global_load_dword v86, v[32:33], off offset:1280
	global_load_dword v87, v[34:35], off offset:1280
	global_load_dword v88, v[32:33], off offset:1536
	global_load_dword v89, v[34:35], off offset:1536
	global_load_dword v90, v[32:33], off offset:1792
	global_load_dword v91, v[34:35], off offset:1792
	global_load_dword v92, v[32:33], off offset:2048
	global_load_dword v93, v[34:35], off offset:2048
	global_load_dword v94, v[32:33], off offset:2304
	global_load_dword v95, v[34:35], off offset:2304
	global_load_dword v96, v[32:33], off offset:2560
	global_load_dword v97, v[34:35], off offset:2560
	global_load_dword v98, v[32:33], off offset:2816
	global_load_dword v99, v[34:35], off offset:2816
	global_load_dword v100, v[32:33], off offset:3072
	global_load_dword v101, v[34:35], off offset:3072
	global_load_dword v102, v[32:33], off offset:3328
	global_load_dword v103, v[34:35], off offset:3328
	global_load_dword v104, v[32:33], off offset:3584
	global_load_dword v105, v[34:35], off offset:3584
	global_load_dword v38, v[32:33], off offset:3840
	global_load_dword v39, v[34:35], off offset:3840
	s_lshl_b32 s4, s6, 3
	s_and_b32 s4, s4, 0xfffff000
	s_lshl_b32 s1, s1, 8
	s_or_b32 s1, s4, s1
	v_or_b32_e32 v56, s1, v65
	v_ashrrev_i32_e32 v57, 31, v56
	v_readlane_b32 s4, v251, 40
	v_readlane_b32 s5, v251, 41
	v_lshlrev_b32_e32 v136, 2, v46
	v_readlane_b32 s14, v253, 19
	v_readlane_b32 s15, v253, 20
	v_readlane_b32 s16, v253, 21
	v_readlane_b32 s17, v253, 22
	v_readlane_b32 s18, v253, 23
	v_readlane_b32 s19, v253, 24
	s_waitcnt vmcnt(0)
	v_pk_mov_b32 v[62:63], v[52:53], v[52:53] op_sel:[1,0]
	s_mov_b32 s11, 0
	v_xor_b32_e32 v77, 0x80000000, v77
	ds_write2st64_b32 v72, v76, v77 offset0:137 offset1:138
	v_xor_b32_e32 v79, 0x80000000, v79
	v_add_u32_e32 v40, 16, v72
	ds_write2st64_b32 v40, v78, v79 offset0:139 offset1:140
	v_xor_b32_e32 v81, 0x80000000, v81
	v_add_u32_e32 v40, 32, v72
	ds_write2st64_b32 v40, v80, v81 offset0:141 offset1:142
	v_xor_b32_e32 v83, 0x80000000, v83
	v_add_u32_e32 v40, 48, v72
	ds_write2st64_b32 v40, v82, v83 offset0:143 offset1:144
	v_xor_b32_e32 v85, 0x80000000, v85
	v_add_u32_e32 v40, 64, v72
	ds_write2st64_b32 v40, v84, v85 offset0:145 offset1:146
	v_xor_b32_e32 v87, 0x80000000, v87
	v_add_u32_e32 v40, 80, v72
	ds_write2st64_b32 v40, v86, v87 offset0:147 offset1:148
	v_xor_b32_e32 v89, 0x80000000, v89
	v_add_u32_e32 v40, 96, v72
	ds_write2st64_b32 v40, v88, v89 offset0:149 offset1:150
	v_xor_b32_e32 v91, 0x80000000, v91
	v_add_u32_e32 v40, 112, v72
	ds_write2st64_b32 v40, v90, v91 offset0:151 offset1:152
	v_xor_b32_e32 v93, 0x80000000, v93
	v_add_u32_e32 v40, 128, v72
	ds_write2st64_b32 v40, v92, v93 offset0:153 offset1:154
	v_xor_b32_e32 v95, 0x80000000, v95
	v_add_u32_e32 v40, 144, v72
	ds_write2st64_b32 v40, v94, v95 offset0:155 offset1:156
	v_xor_b32_e32 v97, 0x80000000, v97
	v_add_u32_e32 v40, 160, v72
	ds_write2st64_b32 v40, v96, v97 offset0:157 offset1:158
	v_xor_b32_e32 v99, 0x80000000, v99
	v_add_u32_e32 v40, 176, v72
	ds_write2st64_b32 v40, v98, v99 offset0:159 offset1:160
	v_xor_b32_e32 v101, 0x80000000, v101
	v_add_u32_e32 v40, 192, v72
	ds_write2st64_b32 v40, v100, v101 offset0:161 offset1:162
	v_xor_b32_e32 v103, 0x80000000, v103
	v_add_u32_e32 v40, 208, v72
	ds_write2st64_b32 v40, v102, v103 offset0:163 offset1:164
	v_xor_b32_e32 v105, 0x80000000, v105
	v_add_u32_e32 v40, 224, v72
	ds_write2st64_b32 v40, v104, v105 offset0:165 offset1:166
	v_xor_b32_e32 v39, 0x80000000, v39
	v_add_u32_e32 v40, 240, v72
	ds_write2st64_b32 v40, v38, v39 offset0:167 offset1:168
	s_waitcnt lgkmcnt(0)
	ds_read_b128 v[106:109], v134 offset:8448
	ds_read_b128 v[110:113], v134 offset:8512
	ds_read_b128 v[114:117], v134 offset:8576
	ds_read_b128 v[118:121], v134 offset:8640
	ds_read_b128 v[122:125], v134 offset:8704
	ds_read_b128 v[126:129], v134 offset:8768
	ds_read_b128 v[130:133], v134 offset:8832
	ds_read_b128 v[144:147], v134 offset:8896
	v_lshlrev_b64 v[32:33], 11, v[56:57]
	v_lshl_add_u64 v[32:33], s[4:5], 0, v[32:33]
	v_readlane_b32 s4, v253, 11
	v_readlane_b32 s5, v253, 12
	s_lshl_b32 s4, s0, 6
	s_mov_b32 s1, s5
	v_lshl_add_u64 v[32:33], v[32:33], 0, s[4:5]
	v_lshl_add_u64 v[32:33], v[32:33], 0, v[136:137]
	global_load_dwordx4 v[32:35], v[32:33], off
	v_writelane_b32 v253, s0, 11
	v_lshl_add_u64 v[58:59], v[48:49], 0, s[4:5]
	v_lshl_add_u64 v[60:61], v[50:51], 0, s[4:5]
	v_writelane_b32 v253, s1, 12
	v_lshl_or_b32 v64, s0, 4, v46
	s_mov_b64 s[0:1], 0
	s_branch .LBB0_334

; #define LAS __attribute__((address_space(3)))
; template <int PASS>
; __device__ __forceinline__ void s5_scan(const Params& p, int l, int widx, int nw, int beff, int nblk, int lane, LAS unsigned char* lds) {
;     ...
;             for (int s = 0; s < 16; ++s) {
;                 const f32x4 u0 = *(LAS f32x4*)(ubc + s * 16), u1 = *(LAS f32x4*)(ubc + s * 16 + 4), u2 = *(LAS f32x4*)(ubc + s * 16 + 8), u3 = *(LAS f32x4*)(ubc + s * 16 + 12);
;                 float bur = 0.f, bui = 0.f;
; #pragma unroll
;                 for (int j = 0; j < 4; ++j) { bur += br[j] * u0[j]; bui += bi[j] * u0[j]; }
; #pragma unroll
;                 for (int j = 0; j < 4; ++j) { bur += br[4 + j] * u1[j]; bui += bi[4 + j] * u1[j]; }
; #pragma unroll
;                 for (int j = 0; j < 4; ++j) { bur += br[8 + j] * u2[j]; bui += bi[8 + j] * u2[j]; }
; #pragma unroll
;                 for (int j = 0; j < 4; ++j) { bur += br[12 + j] * u3[j]; bui += bi[12 + j] * u3[j]; }
;                 const float nxr = ar * xr - ai * xi + bur, nxi = ar * xi + ai * xr + bui; xr = nxr; xi = nxi;
;                 if (PASS == 2) { xb[s * 132 + lane] = xr; xb[s * 132 + 64 + lane] = xi; }
;             }
.LBB0_337:
	v_add_u32_e32 v57, s5, v38
	ds_read_b128 v[40:43], v57
	ds_read_b128 v[66:69], v57 offset:16
	ds_read_b128 v[76:79], v57 offset:32
	ds_read_b128 v[80:83], v57 offset:48
	s_addk_i32 s5, 0x100
	s_waitcnt lgkmcnt(0)
	v_pk_fma_f32 v[36:37], v[8:9], v[40:41], 0 op_sel_hi:[1,0,0]
	s_cmpk_eq_i32 s5, 0x400
	v_pk_fma_f32 v[36:37], v[10:11], v[40:41], v[36:37] op_sel:[0,1,0]
	v_mov_b32_e32 v40, v43
	v_pk_fma_f32 v[36:37], v[4:5], v[42:43], v[36:37] op_sel_hi:[1,0,1]
	v_mov_b32_e32 v42, v69
	v_pk_fma_f32 v[36:37], v[6:7], v[40:41], v[36:37] op_sel_hi:[1,0,1]
	v_pk_mul_f32 v[40:41], v[62:63], v[54:55] op_sel:[0,1]
	v_pk_fma_f32 v[36:37], v[0:1], v[66:67], v[36:37] op_sel_hi:[1,0,1]
	s_nop 0
	v_pk_fma_f32 v[36:37], v[2:3], v[66:67], v[36:37] op_sel:[0,1,0]
	s_nop 0
	v_pk_fma_f32 v[36:37], v[24:25], v[68:69], v[36:37] op_sel_hi:[1,0,1]
	s_nop 0
	v_pk_fma_f32 v[36:37], v[26:27], v[42:43], v[36:37] op_sel_hi:[1,0,1]
	v_mov_b32_e32 v42, v79
	v_pk_fma_f32 v[36:37], v[28:29], v[76:77], v[36:37] op_sel_hi:[1,0,1]
	s_nop 0
	v_pk_fma_f32 v[36:37], v[30:31], v[76:77], v[36:37] op_sel:[0,1,0]
	s_nop 0
	v_pk_fma_f32 v[36:37], v[20:21], v[78:79], v[36:37] op_sel_hi:[1,0,1]
	s_nop 0
	v_pk_fma_f32 v[36:37], v[22:23], v[42:43], v[36:37] op_sel_hi:[1,0,1]
	v_mov_b32_e32 v42, v83
	v_pk_fma_f32 v[36:37], v[16:17], v[80:81], v[36:37] op_sel_hi:[1,0,1]
	s_nop 0
	v_pk_fma_f32 v[36:37], v[18:19], v[80:81], v[36:37] op_sel:[0,1,0]
	s_nop 0
	v_pk_fma_f32 v[36:37], v[12:13], v[82:83], v[36:37] op_sel_hi:[1,0,1]
	s_nop 0
	v_pk_fma_f32 v[36:37], v[14:15], v[42:43], v[36:37] op_sel_hi:[1,0,1]
	v_pk_fma_f32 v[42:43], v[52:53], v[54:55], v[40:41] neg_lo:[0,0,1] neg_hi:[0,0,1]
	v_pk_fma_f32 v[40:41], v[52:53], v[54:55], v[40:41] op_sel_hi:[1,0,1]
	s_nop 0
	v_mov_b32_e32 v43, v41
	v_pk_add_f32 v[36:37], v[42:43], v[36:37]
	ds_write2st64_b32 v39, v36, v37 offset1:1
	ds_read_b128 v[40:43], v57 offset:64
	ds_read_b128 v[66:69], v57 offset:80
	ds_read_b128 v[76:79], v57 offset:96
	ds_read_b128 v[80:83], v57 offset:112
	s_waitcnt lgkmcnt(3)
	v_pk_fma_f32 v[54:55], v[8:9], v[40:41], 0 op_sel_hi:[1,0,0]
	s_nop 0
	v_pk_fma_f32 v[40:41], v[10:11], v[40:41], v[54:55] op_sel:[0,1,0]
	s_waitcnt lgkmcnt(2)
	v_mov_b32_e32 v54, v69
	v_pk_fma_f32 v[40:41], v[4:5], v[42:43], v[40:41] op_sel_hi:[1,0,1]
	v_mov_b32_e32 v42, v43
	v_pk_fma_f32 v[40:41], v[6:7], v[42:43], v[40:41] op_sel_hi:[1,0,1]
	v_pk_mul_f32 v[42:43], v[62:63], v[36:37] op_sel:[0,1]
	v_pk_fma_f32 v[40:41], v[0:1], v[66:67], v[40:41] op_sel_hi:[1,0,1]
	s_nop 0
	v_pk_fma_f32 v[40:41], v[2:3], v[66:67], v[40:41] op_sel:[0,1,0]
	s_nop 0
	v_pk_fma_f32 v[40:41], v[24:25], v[68:69], v[40:41] op_sel_hi:[1,0,1]
	s_nop 0
	v_pk_fma_f32 v[40:41], v[26:27], v[54:55], v[40:41] op_sel_hi:[1,0,1]
	s_waitcnt lgkmcnt(1)
	v_mov_b32_e32 v54, v79
	v_pk_fma_f32 v[40:41], v[28:29], v[76:77], v[40:41] op_sel_hi:[1,0,1]
	s_nop 0
	v_pk_fma_f32 v[40:41], v[30:31], v[76:77], v[40:41] op_sel:[0,1,0]
	s_nop 0
	v_pk_fma_f32 v[40:41], v[20:21], v[78:79], v[40:41] op_sel_hi:[1,0,1]
	s_nop 0
	v_pk_fma_f32 v[40:41], v[22:23], v[54:55], v[40:41] op_sel_hi:[1,0,1]
	s_waitcnt lgkmcnt(0)
	v_mov_b32_e32 v54, v83
	v_pk_fma_f32 v[40:41], v[16:17], v[80:81], v[40:41] op_sel_hi:[1,0,1]
	s_nop 0
	v_pk_fma_f32 v[40:41], v[18:19], v[80:81], v[40:41] op_sel:[0,1,0]
	s_nop 0
	v_pk_fma_f32 v[40:41], v[12:13], v[82:83], v[40:41] op_sel_hi:[1,0,1]
	s_nop 0
	v_pk_fma_f32 v[40:41], v[14:15], v[54:55], v[40:41] op_sel_hi:[1,0,1]
	v_pk_fma_f32 v[54:55], v[52:53], v[36:37], v[42:43] neg_lo:[0,0,1] neg_hi:[0,0,1]
	v_pk_fma_f32 v[36:37], v[52:53], v[36:37], v[42:43] op_sel_hi:[1,0,1]
	s_nop 0
	v_mov_b32_e32 v55, v37
	v_pk_add_f32 v[36:37], v[54:55], v[40:41]
	ds_write2_b32 v39, v36, v37 offset0:132 offset1:196
	ds_read_b128 v[40:43], v57 offset:128
	ds_read_b128 v[66:69], v57 offset:144
	ds_read_b128 v[76:79], v57 offset:160
	ds_read_b128 v[80:83], v57 offset:176
	s_waitcnt lgkmcnt(3)
	v_pk_fma_f32 v[54:55], v[8:9], v[40:41], 0 op_sel_hi:[1,0,0]
	s_nop 0
	v_pk_fma_f32 v[40:41], v[10:11], v[40:41], v[54:55] op_sel:[0,1,0]
	s_waitcnt lgkmcnt(2)
	v_mov_b32_e32 v54, v69
	v_pk_fma_f32 v[40:41], v[4:5], v[42:43], v[40:41] op_sel_hi:[1,0,1]
	v_mov_b32_e32 v42, v43
	v_pk_fma_f32 v[40:41], v[6:7], v[42:43], v[40:41] op_sel_hi:[1,0,1]
	v_pk_mul_f32 v[42:43], v[62:63], v[36:37] op_sel:[0,1]
	v_pk_fma_f32 v[40:41], v[0:1], v[66:67], v[40:41] op_sel_hi:[1,0,1]
	s_nop 0
	v_pk_fma_f32 v[40:41], v[2:3], v[66:67], v[40:41] op_sel:[0,1,0]
	s_nop 0
	v_pk_fma_f32 v[40:41], v[24:25], v[68:69], v[40:41] op_sel_hi:[1,0,1]
	s_nop 0
	v_pk_fma_f32 v[40:41], v[26:27], v[54:55], v[40:41] op_sel_hi:[1,0,1]
	s_waitcnt lgkmcnt(1)
	v_mov_b32_e32 v54, v79
	v_pk_fma_f32 v[40:41], v[28:29], v[76:77], v[40:41] op_sel_hi:[1,0,1]
	s_nop 0
	v_pk_fma_f32 v[40:41], v[30:31], v[76:77], v[40:41] op_sel:[0,1,0]
	s_nop 0
	v_pk_fma_f32 v[40:41], v[20:21], v[78:79], v[40:41] op_sel_hi:[1,0,1]
	s_nop 0
	v_pk_fma_f32 v[40:41], v[22:23], v[54:55], v[40:41] op_sel_hi:[1,0,1]
	s_waitcnt lgkmcnt(0)
	v_mov_b32_e32 v54, v83
	v_pk_fma_f32 v[40:41], v[16:17], v[80:81], v[40:41] op_sel_hi:[1,0,1]
	s_nop 0
	v_pk_fma_f32 v[40:41], v[18:19], v[80:81], v[40:41] op_sel:[0,1,0]
	s_nop 0
	v_pk_fma_f32 v[40:41], v[12:13], v[82:83], v[40:41] op_sel_hi:[1,0,1]
	s_nop 0
	v_pk_fma_f32 v[40:41], v[14:15], v[54:55], v[40:41] op_sel_hi:[1,0,1]
	v_pk_fma_f32 v[54:55], v[52:53], v[36:37], v[42:43] neg_lo:[0,0,1] neg_hi:[0,0,1]
	v_pk_fma_f32 v[36:37], v[52:53], v[36:37], v[42:43] op_sel_hi:[1,0,1]
	s_nop 0
	v_mov_b32_e32 v55, v37
	v_pk_add_f32 v[36:37], v[54:55], v[40:41]
	v_add_u32_e32 v40, 32, v39
	ds_write2st64_b32 v40, v36, v37 offset0:4 offset1:5
	ds_read_b128 v[40:43], v57 offset:192
	ds_read_b128 v[66:69], v57 offset:208
	ds_read_b128 v[76:79], v57 offset:224
	ds_read_b128 v[80:83], v57 offset:240
	s_waitcnt lgkmcnt(3)
; #define LAS __attribute__((address_space(3)))
; #define WAVE_SYNC() asm volatile("s_waitcnt lgkmcnt(0)" ::: "memory")
; __device__ __forceinline__ float dot4(f32x4 a, f32x4 b) { return (a.x * b.x + a.y * b.y) + (a.z * b.z + a.w * b.w); }
; __device__ __forceinline__ float gelu_tanh(float x) { const float t = tanhf(0.7978845608028654f * (x + 0.044715f * x * x * x)); return 0.5f * x * (1.0f + t); }
; template <int PASS>
; __device__ __forceinline__ void s5_scan(const Params& p, int l, int widx, int nw, int beff, int nblk, int lane, LAS unsigned char* lds) {
;     ...
;             }
;             if (PASS == 2) {
;                 WAVE_SYNC();
;                 const int s = lane >> 2, c4 = lane & 3;
;                 f32x4 y = {0.f, 0.f, 0.f, 0.f};
; #pragma unroll 4
;                 for (int n4 = 0; n4 < 32; ++n4) {
;                     const f32x4 xv = *(LAS f32x4*)(xb + s * 132 + n4 * 4);
; #pragma unroll
;                     for (int j = 0; j < 4; ++j) { const f32x4 cv = *(LAS f32x4*)(ct + (c4 * 4 + j) * 132 + n4 * 4); y[j] += dot4(xv, cv); }
;                 }
;                 const f32x4 uu = *(LAS f32x4*)(ubc + s * 16 + c4 * 4);
;                 const f32x4 dsk = *(const f32x4*)(p.in[30] + l * 512 + g * 16 + c4 * 4);
;                 y = y + dsk * uu;
;                 y.x = gelu_tanh(y.x); y.y = gelu_tanh(y.y); y.z = gelu_tanh(y.z); y.w = gelu_tanh(y.w);
;                 const size_t o = (size_t)(m0 + bt * 16 + s) * 512 + g * 16 + c4 * 4;
;                 *(f32x4*)(YS + o) = y;
	v_pk_fma_f32 v[54:55], v[8:9], v[40:41], 0 op_sel_hi:[1,0,0]
	s_nop 0
	v_pk_fma_f32 v[40:41], v[10:11], v[40:41], v[54:55] op_sel:[0,1,0]
	s_waitcnt lgkmcnt(2)
	v_mov_b32_e32 v54, v69
	v_pk_fma_f32 v[40:41], v[4:5], v[42:43], v[40:41] op_sel_hi:[1,0,1]
	v_mov_b32_e32 v42, v43
	v_pk_fma_f32 v[40:41], v[6:7], v[42:43], v[40:41] op_sel_hi:[1,0,1]
	v_pk_mul_f32 v[42:43], v[62:63], v[36:37] op_sel:[0,1]
	v_pk_fma_f32 v[40:41], v[0:1], v[66:67], v[40:41] op_sel_hi:[1,0,1]
	s_nop 0
	v_pk_fma_f32 v[40:41], v[2:3], v[66:67], v[40:41] op_sel:[0,1,0]
	s_nop 0
	v_pk_fma_f32 v[40:41], v[24:25], v[68:69], v[40:41] op_sel_hi:[1,0,1]
	s_nop 0
	v_pk_fma_f32 v[40:41], v[26:27], v[54:55], v[40:41] op_sel_hi:[1,0,1]
	s_waitcnt lgkmcnt(1)
	v_mov_b32_e32 v54, v79
	v_pk_fma_f32 v[40:41], v[28:29], v[76:77], v[40:41] op_sel_hi:[1,0,1]
	s_nop 0
	v_pk_fma_f32 v[40:41], v[30:31], v[76:77], v[40:41] op_sel:[0,1,0]
	s_nop 0
	v_pk_fma_f32 v[40:41], v[20:21], v[78:79], v[40:41] op_sel_hi:[1,0,1]
	s_nop 0
	v_pk_fma_f32 v[40:41], v[22:23], v[54:55], v[40:41] op_sel_hi:[1,0,1]
	s_waitcnt lgkmcnt(0)
	v_mov_b32_e32 v54, v83
	v_pk_fma_f32 v[40:41], v[16:17], v[80:81], v[40:41] op_sel_hi:[1,0,1]
	s_nop 0
	v_pk_fma_f32 v[40:41], v[18:19], v[80:81], v[40:41] op_sel:[0,1,0]
	s_nop 0
	v_pk_fma_f32 v[40:41], v[12:13], v[82:83], v[40:41] op_sel_hi:[1,0,1]
	s_nop 0
	v_pk_fma_f32 v[40:41], v[14:15], v[54:55], v[40:41] op_sel_hi:[1,0,1]
	v_pk_fma_f32 v[54:55], v[52:53], v[36:37], v[42:43] neg_lo:[0,0,1] neg_hi:[0,0,1]
	v_pk_fma_f32 v[36:37], v[52:53], v[36:37], v[42:43] op_sel_hi:[1,0,1]
	s_nop 0
	v_mov_b32_e32 v55, v37
	v_pk_add_f32 v[54:55], v[54:55], v[40:41]
	v_add_u32_e32 v36, 48, v39
	v_add_u32_e32 v39, 0x840, v39
	ds_write2st64_b32 v36, v54, v55 offset0:6 offset1:7
	s_cbranch_scc0 .LBB0_337
	s_waitcnt lgkmcnt(0)
	v_mov_b32_e32 v84, 0
	v_mov_b32_e32 v85, 0
	v_mov_b32_e32 v86, 0
	v_mov_b32_e32 v87, 0
	ds_read_b128 v[148:151], v134
	ds_read_b128 v[152:155], v134 offset:64
	ds_read_b128 v[158:161], v134 offset:128
	ds_read_b128 v[162:165], v134 offset:192
	ds_read_b128 v[166:169], v134 offset:256
	ds_read_b128 v[170:173], v134 offset:320
	ds_read_b128 v[174:177], v134 offset:384
	ds_read_b128 v[178:181], v134 offset:448
	s_waitcnt lgkmcnt(7)
	v_mfma_f32_16x16x4_f32 v[84:87], v148, v106, v[84:87]
	v_mfma_f32_16x16x4_f32 v[84:87], v149, v107, v[84:87]
	v_mfma_f32_16x16x4_f32 v[84:87], v150, v108, v[84:87]
	v_mfma_f32_16x16x4_f32 v[84:87], v151, v109, v[84:87]
	s_waitcnt lgkmcnt(6)
	v_mfma_f32_16x16x4_f32 v[84:87], v152, v110, v[84:87]
	v_mfma_f32_16x16x4_f32 v[84:87], v153, v111, v[84:87]
	v_mfma_f32_16x16x4_f32 v[84:87], v154, v112, v[84:87]
	v_mfma_f32_16x16x4_f32 v[84:87], v155, v113, v[84:87]
	s_waitcnt lgkmcnt(5)
	v_mfma_f32_16x16x4_f32 v[84:87], v158, v114, v[84:87]
	v_mfma_f32_16x16x4_f32 v[84:87], v159, v115, v[84:87]
	v_mfma_f32_16x16x4_f32 v[84:87], v160, v116, v[84:87]
	v_mfma_f32_16x16x4_f32 v[84:87], v161, v117, v[84:87]
	s_waitcnt lgkmcnt(4)
	v_mfma_f32_16x16x4_f32 v[84:87], v162, v118, v[84:87]
	v_mfma_f32_16x16x4_f32 v[84:87], v163, v119, v[84:87]
	v_mfma_f32_16x16x4_f32 v[84:87], v164, v120, v[84:87]
	v_mfma_f32_16x16x4_f32 v[84:87], v165, v121, v[84:87]
	s_waitcnt lgkmcnt(3)
	v_mfma_f32_16x16x4_f32 v[84:87], v166, v122, v[84:87]
	v_mfma_f32_16x16x4_f32 v[84:87], v167, v123, v[84:87]
	v_mfma_f32_16x16x4_f32 v[84:87], v168, v124, v[84:87]
	v_mfma_f32_16x16x4_f32 v[84:87], v169, v125, v[84:87]
	s_waitcnt lgkmcnt(2)
	v_mfma_f32_16x16x4_f32 v[84:87], v170, v126, v[84:87]
	v_mfma_f32_16x16x4_f32 v[84:87], v171, v127, v[84:87]
	v_mfma_f32_16x16x4_f32 v[84:87], v172, v128, v[84:87]
	v_mfma_f32_16x16x4_f32 v[84:87], v173, v129, v[84:87]
	s_waitcnt lgkmcnt(1)
	v_mfma_f32_16x16x4_f32 v[84:87], v174, v130, v[84:87]
	v_mfma_f32_16x16x4_f32 v[84:87], v175, v131, v[84:87]
	v_mfma_f32_16x16x4_f32 v[84:87], v176, v132, v[84:87]
	v_mfma_f32_16x16x4_f32 v[84:87], v177, v133, v[84:87]
	s_waitcnt lgkmcnt(0)
	v_mfma_f32_16x16x4_f32 v[84:87], v178, v144, v[84:87]
	v_mfma_f32_16x16x4_f32 v[84:87], v179, v145, v[84:87]
	v_mfma_f32_16x16x4_f32 v[84:87], v180, v146, v[84:87]
	v_mfma_f32_16x16x4_f32 v[84:87], v181, v147, v[84:87]
	s_nop 7
	s_nop 3
	ds_write_b32 v135, v84
	ds_write_b32 v135, v85 offset:64
	ds_write_b32 v135, v86 offset:128
	ds_write_b32 v135, v87 offset:192
	s_waitcnt lgkmcnt(0)
	ds_read_b64 v[68:69], v138
	ds_read_b64 v[66:67], v138 offset:8
	global_load_dwordx4 v[36:39], v[60:61], off
	v_add3_u32 v40, s4, v71, v136
	ds_read_b128 v[40:43], v40 offset:24576
	s_mov_b32 s3, 0x3f200000
	s_waitcnt vmcnt(0) lgkmcnt(0)
	v_pk_fma_f32 v[36:37], v[40:41], v[36:37], v[68:69]
	s_nop 0
	v_mul_f32_e32 v40, 0x3d372713, v36
	v_mul_f32_e32 v40, v36, v40
	v_fma_f32 v40, v36, v40, v36
	v_mul_f32_e32 v40, 0x3f4c422a, v40
	v_cmp_nlt_f32_e64 s[4:5], |v40|, s3
	s_and_saveexec_b64 s[12:13], s[4:5]
	s_xor_b64 s[4:5], exec, s[12:13]
	s_cbranch_execz .LBB0_342
	v_add_f32_e64 v41, |v40|, |v40|
	v_mul_f32_e32 v57, 0x3fb8aa3b, v41
	v_rndne_f32_e32 v68, v57
	s_mov_b32 s3, 0x3fb8aa3b
	v_sub_f32_e32 v69, v57, v68
	v_fma_f32 v57, v41, s3, -v57
	v_fmac_f32_e32 v57, 0x32a5705f, v41
	v_add_f32_e32 v57, v69, v57
	v_cvt_i32_f32_e32 v68, v68
	v_exp_f32_e32 v57, v57
	s_mov_b32 s3, 0xc2ce8ed0
	v_cmp_ngt_f32_e32 vcc, s3, v41
	s_mov_b32 s3, 0x42b17218
	v_ldexp_f32 v57, v57, v68
	v_cndmask_b32_e32 v57, 0, v57, vcc
	v_cmp_nlt_f32_e32 vcc, s3, v41
	s_nop 1
	v_cndmask_b32_e32 v41, v194, v57, vcc
	v_add_f32_e32 v41, 1.0, v41
	v_rcp_f32_e32 v41, v41
	s_nop 0
	v_fma_f32 v41, v41, -2.0, 1.0
